# attention row-max across wave halves via v_permlane32_swap instead of a ds_bpermute round trip per key tile; on top of scan helper priority raise
# speedup vs baseline: 1.0160x; 1.0015x over previous
; #define LAS __attribute__((address_space(3)))
; DI unsigned pk2(float lo, float hi) { f32x2 v = {lo, hi}; bf16x2_t b = __builtin_convertvector(v, bf16x2_t); return __builtin_bit_cast(unsigned, b); }
; DI void attn_item(LAS unsigned char* lds, const Ctx& c, int bh, int qb) {
;     ...
;             const LAS unsigned char* Kb = lds + AT_K + bf * AT_KSZ; const LAS unsigned char* Vb = lds + AT_V + bf * AT_VSZ;
;             f32x16 s0, s1;
; #pragma unroll
;             for (int r = 0; r < 16; ++r) { s0[r] = 0.f; s1[r] = 0.f; }
; #pragma unroll
;             for (int t = 0; t < 12; ++t) {
;                 const bf16x8 k0 = *(const LAS bf16x8*)(Kb + q * 400 + (16 * t + 8 * g) * 2);
;                 const bf16x8 k1 = *(const LAS bf16x8*)(Kb + (32 + q) * 400 + (16 * t + 8 * g) * 2);
;                 s0 = __builtin_amdgcn_mfma_f32_32x32x16_bf16(k0, qf[t], s0, 0, 0, 0);
;                 s1 = __builtin_amdgcn_mfma_f32_32x32x16_bf16(k1, qf[t], s1, 0, 0, 0);
;             }
;             float mx = s0[0];
; #pragma unroll
;             for (int r = 1; r < 16; ++r) mx = fmaxf(mx, s0[r]);
; #pragma unroll
;             for (int r = 0; r < 16; ++r) mx = fmaxf(mx, s1[r]);
;             mx = fmaxf(mx, __shfl_xor(mx, 32));
;             const float m_new = fmaxf(m_run, mx), alpha = __builtin_amdgcn_exp2f(m_run - m_new);
;             float ps = 0.f;
; #pragma unroll
;             for (int r = 0; r < 16; ++r) { s0[r] = __builtin_amdgcn_exp2f(s0[r] - m_new); s1[r] = __builtin_amdgcn_exp2f(s1[r] - m_new); ps += s0[r] + s1[r]; }
;             l_run = l_run * alpha + ps; m_run = m_new;
; #pragma unroll
;             for (int i = 0; i < 4; ++i)
; #pragma unroll
;                 for (int r = 0; r < 16; ++r) oacc[i][r] *= alpha;
; #pragma unroll
;             for (int t = 0; t < 4; ++t) { const f32x16& sx = (t < 2) ? s0 : s1; const int o8 = 8 * (t & 1); u32x4 pw;
;                 pw.x = pk2(sx[o8 + 0], sx[o8 + 1]); pw.y = pk2(sx[o8 + 2], sx[o8 + 3]); pw.z = pk2(sx[o8 + 4], sx[o8 + 5]); pw.w = pk2(sx[o8 + 6], sx[o8 + 7]); const bf16x8 pb = __builtin_bit_cast(bf16x8, pw);
.LBB0_187:
	s_mul_i32 s14, s11, 0x6400
	v_add_u32_e32 v0, s14, v216
	ds_read_b128 v[66:69], v0
	ds_read_b128 v[70:73], v0 offset:32
	ds_read_b128 v[74:77], v0 offset:64
	ds_read_b128 v[78:81], v0 offset:96
	ds_read_b128 v[220:223], v0 offset:128
	ds_read_b128 v[236:239], v0 offset:160
	ds_read_b128 v[240:243], v0 offset:192
	ds_read_b128 v[244:247], v0 offset:224
	v_and_b32_e32 v199, 64, v230
	v_add_u32_e32 v199, 64, v199
	s_mul_i32 s14, s11, 0x4400
	s_waitcnt lgkmcnt(7)
	v_mfma_f32_32x32x16_bf16 v[82:97], v[66:69], v[98:101], 0
	ds_read_b128 v[66:69], v0 offset:256
	v_add_u32_e32 v224, s14, v217
	v_add_u32_e32 v225, 0xc800, v224
	v_add_u32_e32 v226, 0xd800, v224
	v_add_u32_e32 v228, 0xe800, v224
	v_add_u32_e32 v224, 0xf800, v224
	s_waitcnt lgkmcnt(7)
	v_mfma_f32_32x32x16_bf16 v[82:97], v[70:73], v[102:105], v[82:97]
	ds_read_b128 v[70:73], v0 offset:288
	s_waitcnt lgkmcnt(7)
	v_mfma_f32_32x32x16_bf16 v[82:97], v[74:77], v[106:109], v[82:97]
	ds_read_b128 v[74:77], v0 offset:320
	s_waitcnt lgkmcnt(7)
	v_mfma_f32_32x32x16_bf16 v[82:97], v[78:81], v[110:113], v[82:97]
	ds_read_b128 v[78:81], v0 offset:352
	s_waitcnt lgkmcnt(7)
	v_mfma_f32_32x32x16_bf16 v[82:97], v[220:223], v[114:117], v[82:97]
	ds_read_b128 v[220:223], v0 offset:12800
	s_waitcnt lgkmcnt(7)
	v_mfma_f32_32x32x16_bf16 v[82:97], v[236:239], v[118:121], v[82:97]
	ds_read_b128 v[236:239], v0 offset:12832
	s_waitcnt lgkmcnt(7)
	v_mfma_f32_32x32x16_bf16 v[82:97], v[240:243], v[122:125], v[82:97]
	ds_read_b128 v[240:243], v0 offset:12864
	s_waitcnt lgkmcnt(7)
	v_mfma_f32_32x32x16_bf16 v[82:97], v[244:247], v[126:129], v[82:97]
	ds_read_b128 v[244:247], v0 offset:12896
	s_waitcnt lgkmcnt(7)
	v_mfma_f32_32x32x16_bf16 v[82:97], v[66:69], v[134:137], v[82:97]
	s_waitcnt lgkmcnt(6)
	v_mfma_f32_32x32x16_bf16 v[82:97], v[70:73], v[138:141], v[82:97]
	s_waitcnt lgkmcnt(5)
	v_mfma_f32_32x32x16_bf16 v[82:97], v[74:77], v[142:145], v[82:97]
	s_waitcnt lgkmcnt(4)
	v_mfma_f32_32x32x16_bf16 v[82:97], v[78:81], v[146:149], v[82:97]
	s_waitcnt lgkmcnt(3)
	v_mfma_f32_32x32x16_bf16 v[66:81], v[220:223], v[98:101], 0
	ds_read_b128 v[220:223], v0 offset:12928
	s_nop 9
	v_max_f32_e32 v198, v82, v82
	s_waitcnt lgkmcnt(3)
	v_mfma_f32_32x32x16_bf16 v[66:81], v[236:239], v[102:105], v[66:81]
	ds_read_b128 v[236:239], v0 offset:12960
	s_waitcnt lgkmcnt(3)
	v_mfma_f32_32x32x16_bf16 v[66:81], v[240:243], v[106:109], v[66:81]
	ds_read_b128 v[240:243], v0 offset:12992
	s_waitcnt lgkmcnt(3)
	v_mfma_f32_32x32x16_bf16 v[66:81], v[244:247], v[110:113], v[66:81]
	ds_read_b128 v[244:247], v0 offset:13024
	s_waitcnt lgkmcnt(3)
	v_mfma_f32_32x32x16_bf16 v[66:81], v[220:223], v[114:117], v[66:81]
	ds_read_b128 v[220:223], v0 offset:13056
	s_waitcnt lgkmcnt(3)
	v_mfma_f32_32x32x16_bf16 v[66:81], v[236:239], v[118:121], v[66:81]
	ds_read_b128 v[236:239], v0 offset:13088
	s_waitcnt lgkmcnt(3)
	v_mfma_f32_32x32x16_bf16 v[66:81], v[240:243], v[122:125], v[66:81]
	s_waitcnt lgkmcnt(2)
	v_mfma_f32_32x32x16_bf16 v[66:81], v[244:247], v[126:129], v[66:81]
	s_waitcnt lgkmcnt(1)
	v_mfma_f32_32x32x16_bf16 v[66:81], v[220:223], v[134:137], v[66:81]
	s_waitcnt lgkmcnt(0)
	v_mfma_f32_32x32x16_bf16 v[66:81], v[236:239], v[138:141], v[66:81]
	ds_read_b128 v[220:223], v0 offset:13120
	ds_read_b128 v[236:239], v0 offset:13152
	v_max_f32_e32 v0, v83, v83
	v_max_f32_e32 v0, v198, v0
	v_max3_f32 v0, v0, v84, v85
	v_max3_f32 v0, v0, v86, v87
	v_max3_f32 v0, v0, v88, v89
	v_max3_f32 v0, v0, v90, v91
	s_waitcnt lgkmcnt(1)
	v_mfma_f32_32x32x16_bf16 v[66:81], v[220:223], v[142:145], v[66:81]
	v_max3_f32 v0, v0, v92, v93
	v_max3_f32 v0, v0, v94, v95
	v_max3_f32 v0, v0, v96, v97
	v_xor_b32_e32 v198, 32, v230
	v_cmp_lt_i32_e32 vcc, v198, v199
	ds_read2_b64 v[220:223], v226 offset0:32 offset1:34
	s_waitcnt lgkmcnt(1)
	v_mfma_f32_32x32x16_bf16 v[66:81], v[236:239], v[146:149], v[66:81]
	v_cndmask_b32_e32 v198, v230, v198, vcc
	v_lshlrev_b32_e32 v198, 2, v198
	s_nop 9
	v_max3_f32 v0, v0, v66, v67
	v_max3_f32 v0, v0, v68, v69
	v_max3_f32 v0, v0, v70, v71
	v_max3_f32 v0, v0, v72, v73
	v_max3_f32 v0, v0, v74, v75
	v_max3_f32 v0, v0, v76, v77
	v_max3_f32 v0, v0, v78, v79
	v_max3_f32 v0, v0, v80, v81
	v_mov_b32_e32 v198, v0
	v_mov_b32_e32 v229, v0
	s_nop 1
	v_permlane32_swap_b32_e32 v198, v229
	v_max3_f32 v219, v210, v198, v229
	v_sub_f32_e32 v0, v82, v219
	v_exp_f32_e32 v198, v0
	v_sub_f32_e32 v0, v66, v219
	v_sub_f32_e32 v66, v83, v219
	v_exp_f32_e32 v201, v66
	v_sub_f32_e32 v66, v67, v219
	v_exp_f32_e32 v203, v66
	v_sub_f32_e32 v66, v84, v219
	v_exp_f32_e32 v204, v66
	v_sub_f32_e32 v66, v68, v219
	v_exp_f32_e32 v205, v66
	v_sub_f32_e32 v66, v85, v219
	v_exp_f32_e32 v68, v66
	v_sub_f32_e32 v66, v86, v219
	v_sub_f32_e32 v82, v90, v219
	v_sub_f32_e32 v84, v92, v219
	v_exp_f32_e32 v211, v66
	v_sub_f32_e32 v66, v87, v219
	v_exp_f32_e32 v83, v82
	v_sub_f32_e32 v82, v91, v219
	v_exp_f32_e32 v85, v84
	v_sub_f32_e32 v84, v93, v219
	ds_read2_b64 v[90:93], v225 offset1:2
	v_exp_f32_e32 v202, v0
	v_sub_f32_e32 v0, v210, v219
	v_exp_f32_e32 v210, v66
	v_sub_f32_e32 v66, v88, v219
	v_exp_f32_e32 v67, v66
	v_sub_f32_e32 v66, v89, v219
	v_exp_f32_e32 v66, v66
	v_exp_f32_e32 v0, v0
	v_sub_f32_e32 v88, v96, v219
	v_add_f32_e32 v200, v198, v202
	v_sub_f32_e32 v86, v94, v219
	v_exp_f32_e32 v89, v88
	v_sub_f32_e32 v88, v97, v219
	v_cvt_pk_bf16_f32 v94, v198, v201
	v_pk_mov_b32 v[96:97], v[210:211], v[210:211] op_sel:[1,0]
	v_pk_mov_b32 v[198:199], v[66:67], v[66:67] op_sel:[1,0]
	v_exp_f32_e32 v87, v86
	v_sub_f32_e32 v86, v95, v219
	v_pk_mul_f32 v[64:65], v[64:65], v[0:1] op_sel_hi:[1,0]
	v_pk_mul_f32 v[62:63], v[62:63], v[0:1] op_sel_hi:[1,0]
	v_pk_mul_f32 v[60:61], v[60:61], v[0:1] op_sel_hi:[1,0]
	v_pk_mul_f32 v[58:59], v[58:59], v[0:1] op_sel_hi:[1,0]
	v_pk_mul_f32 v[56:57], v[56:57], v[0:1] op_sel_hi:[1,0]
	v_pk_mul_f32 v[54:55], v[54:55], v[0:1] op_sel_hi:[1,0]
	v_pk_mul_f32 v[52:53], v[52:53], v[0:1] op_sel_hi:[1,0]
	v_pk_mul_f32 v[50:51], v[50:51], v[0:1] op_sel_hi:[1,0]
	v_cvt_pk_bf16_f32 v95, v204, v68
	v_cvt_pk_bf16_f32 v96, v96, v97
	v_cvt_pk_bf16_f32 v97, v198, v199
	v_pk_mul_f32 v[48:49], v[48:49], v[0:1] op_sel_hi:[1,0]
	v_pk_mul_f32 v[46:47], v[46:47], v[0:1] op_sel_hi:[1,0]
	s_waitcnt lgkmcnt(0)
; #define LAS __attribute__((address_space(3)))
; DI unsigned pk2(float lo, float hi) { f32x2 v = {lo, hi}; bf16x2_t b = __builtin_convertvector(v, bf16x2_t); return __builtin_bit_cast(unsigned, b); }
; DI void attn_item(LAS unsigned char* lds, const Ctx& c, int bh, int qb) {
;     ...
;             const float m_new = fmaxf(m_run, mx), alpha = __builtin_amdgcn_exp2f(m_run - m_new);
;             float ps = 0.f;
; #pragma unroll
;             for (int r = 0; r < 16; ++r) { s0[r] = __builtin_amdgcn_exp2f(s0[r] - m_new); s1[r] = __builtin_amdgcn_exp2f(s1[r] - m_new); ps += s0[r] + s1[r]; }
;             l_run = l_run * alpha + ps; m_run = m_new;
; #pragma unroll
;             for (int i = 0; i < 4; ++i)
; #pragma unroll
;                 for (int r = 0; r < 16; ++r) oacc[i][r] *= alpha;
; #pragma unroll
;             for (int t = 0; t < 4; ++t) { const f32x16& sx = (t < 2) ? s0 : s1; const int o8 = 8 * (t & 1); u32x4 pw;
;                 pw.x = pk2(sx[o8 + 0], sx[o8 + 1]); pw.y = pk2(sx[o8 + 2], sx[o8 + 3]); pw.z = pk2(sx[o8 + 4], sx[o8 + 5]); pw.w = pk2(sx[o8 + 6], sx[o8 + 7]); const bf16x8 pb = __builtin_bit_cast(bf16x8, pw);
; #pragma unroll
;                 for (int md = 0; md < 4; ++md) {
;                     const LAS unsigned char* vp = Vb + (32 * md + q) * 136 + (16 * t + 4 * g) * 2;
;                     const s16x4 a = *(const LAS s16x4*)vp, bb = *(const LAS s16x4*)(vp + 16);
;                     oacc[md] = __builtin_amdgcn_mfma_f32_32x32x16_bf16(__builtin_shufflevector(a, bb, 0, 1, 2, 3, 4, 5, 6, 7), pb, oacc[md], 0, 0, 0);
;                 } }
	v_mfma_f32_32x32x16_bf16 v[50:65], v[90:93], v[94:97], v[50:65]
	ds_read2_b64 v[90:93], v228 offset0:64 offset1:66
	v_mul_f32_e64 v44, v44, v0
	v_mul_f32_e64 v45, v45, v0
	v_mul_f32_e64 v42, v42, v0
	v_mul_f32_e64 v43, v43, v0
	v_pk_mul_f32 v[40:41], v[40:41], v[0:1] op_sel_hi:[1,0]
	v_pk_mul_f32 v[38:39], v[38:39], v[0:1] op_sel_hi:[1,0]
	v_pk_mul_f32 v[36:37], v[36:37], v[0:1] op_sel_hi:[1,0]
	v_pk_mul_f32 v[34:35], v[34:35], v[0:1] op_sel_hi:[1,0]
	v_exp_f32_e32 v84, v84
	v_exp_f32_e32 v86, v86
	v_mfma_f32_32x32x16_bf16 v[34:49], v[220:223], v[94:97], v[34:49]
	ds_read2_b64 v[220:223], v224 offset0:96 offset1:98
	v_mul_f32_e64 v32, v32, v0
	v_mul_f32_e64 v33, v33, v0
	v_mul_f32_e64 v30, v30, v0
	v_mul_f32_e64 v31, v31, v0
	v_pk_mul_f32 v[28:29], v[28:29], v[0:1] op_sel_hi:[1,0]
	v_pk_mul_f32 v[26:27], v[26:27], v[0:1] op_sel_hi:[1,0]
	v_pk_mul_f32 v[24:25], v[24:25], v[0:1] op_sel_hi:[1,0]
	v_pk_mul_f32 v[22:23], v[22:23], v[0:1] op_sel_hi:[1,0]
	v_pk_mul_f32 v[20:21], v[20:21], v[0:1] op_sel_hi:[1,0]
	v_pk_mul_f32 v[18:19], v[18:19], v[0:1] op_sel_hi:[1,0]
	v_exp_f32_e32 v88, v88
	v_pk_mul_f32 v[16:17], v[16:17], v[0:1] op_sel_hi:[1,0]
	s_waitcnt lgkmcnt(1)
	v_mfma_f32_32x32x16_bf16 v[18:33], v[90:93], v[94:97], v[18:33]
	ds_read2_b64 v[90:93], v225 offset0:4 offset1:6
	v_mul_f32_e64 v14, v14, v0
	v_mul_f32_e64 v15, v15, v0
	v_mul_f32_e64 v12, v12, v0
	v_mul_f32_e64 v13, v13, v0
	v_pk_mul_f32 v[10:11], v[10:11], v[0:1] op_sel_hi:[1,0]
	v_pk_mul_f32 v[8:9], v[8:9], v[0:1] op_sel_hi:[1,0]
	v_pk_mul_f32 v[6:7], v[6:7], v[0:1] op_sel_hi:[1,0]
	v_pk_mul_f32 v[4:5], v[4:5], v[0:1] op_sel_hi:[1,0]
	v_pk_mul_f32 v[2:3], v[2:3], v[0:1] op_sel_hi:[1,0]
	v_exp_f32_e32 v82, v82
	v_sub_f32_e32 v69, v69, v219
	s_waitcnt lgkmcnt(1)
	v_mfma_f32_32x32x16_bf16 v[2:17], v[220:223], v[94:97], v[2:17]
	v_pk_mov_b32 v[94:95], v[84:85], v[84:85] op_sel:[1,0]
	v_pk_mov_b32 v[198:199], v[82:83], v[82:83] op_sel:[1,0]
	v_cvt_pk_bf16_f32 v237, v94, v95
	v_pk_mov_b32 v[94:95], v[86:87], v[86:87] op_sel:[1,0]
	v_cvt_pk_bf16_f32 v236, v198, v199
	v_cvt_pk_bf16_f32 v238, v94, v95
	v_pk_mov_b32 v[94:95], v[88:89], v[88:89] op_sel:[1,0]
	v_add_f32_e32 v199, v204, v205
	v_cvt_pk_bf16_f32 v239, v94, v95
	ds_read2_b64 v[94:97], v226 offset0:36 offset1:38
	v_exp_f32_e32 v204, v69
	s_waitcnt lgkmcnt(1)
	v_mfma_f32_32x32x16_bf16 v[50:65], v[90:93], v[236:239], v[50:65]
	v_add_f32_e32 v90, 0, v200
	v_add_f32_e32 v91, v201, v203
	v_add_f32_e32 v198, v91, v90
	ds_read2_b64 v[90:93], v228 offset0:68 offset1:70
	v_sub_f32_e32 v72, v72, v219
	v_exp_f32_e32 v201, v72
	v_sub_f32_e32 v72, v73, v219
	s_waitcnt lgkmcnt(1)
	v_mfma_f32_32x32x16_bf16 v[34:49], v[94:97], v[236:239], v[34:49]
	v_add_f32_e32 v97, v68, v204
	v_sub_f32_e32 v68, v70, v219
	v_exp_f32_e32 v95, v68
	v_sub_f32_e32 v68, v71, v219
	v_exp_f32_e32 v94, v68
	ds_read2_b64 v[68:71], v224 offset0:100 offset1:102
	v_exp_f32_e32 v200, v72
	s_waitcnt lgkmcnt(1)
	v_mfma_f32_32x32x16_bf16 v[18:33], v[90:93], v[236:239], v[18:33]
	ds_read2_b64 v[90:93], v225 offset0:8 offset1:10
	v_add_f32_e32 v96, v199, v198
	v_add_f32_e32 v220, v97, v96
	v_add_f32_e64 v198, v210, v94
	v_add_f32_e64 v199, v211, v95
	v_pk_mov_b32 v[72:73], v[200:201], v[200:201] op_sel:[1,0]
	v_sub_f32_e32 v76, v76, v219
	v_add_f32_e32 v199, v199, v220
	s_waitcnt lgkmcnt(1)
	v_mfma_f32_32x32x16_bf16 v[2:17], v[68:71], v[236:239], v[2:17]
	v_pk_mov_b32 v[70:71], v[94:95], v[94:95] op_sel:[1,0]
	ds_read2_b64 v[94:97], v226 offset0:40 offset1:42
	v_cvt_pk_bf16_f32 v68, v202, v203
	v_cvt_pk_bf16_f32 v69, v205, v204
	v_cvt_pk_bf16_f32 v70, v70, v71
	v_cvt_pk_bf16_f32 v71, v72, v73
	v_sub_f32_e32 v72, v74, v219
	v_pk_add_f32 v[66:67], v[66:67], v[200:201]
	s_waitcnt lgkmcnt(1)
	v_mfma_f32_32x32x16_bf16 v[50:65], v[90:93], v[68:71], v[50:65]
	v_exp_f32_e32 v91, v72
	v_sub_f32_e32 v72, v75, v219
	v_exp_f32_e32 v90, v72
	ds_read2_b64 v[72:75], v228 offset0:72 offset1:74
	v_exp_f32_e32 v93, v76
	v_sub_f32_e32 v76, v77, v219
	v_exp_f32_e32 v92, v76
	v_sub_f32_e32 v76, v78, v219
	s_waitcnt lgkmcnt(1)
	v_mfma_f32_32x32x16_bf16 v[34:49], v[94:97], v[68:71], v[34:49]
	v_exp_f32_e32 v95, v76
	v_sub_f32_e32 v94, v79, v219
	ds_read2_b64 v[76:79], v224 offset0:104 offset1:106
	v_exp_f32_e32 v94, v94
	v_mov_b32_e32 v210, v219
	s_waitcnt lgkmcnt(1)
	v_mfma_f32_32x32x16_bf16 v[18:33], v[72:75], v[68:71], v[18:33]
	v_sub_f32_e32 v72, v80, v219
	v_exp_f32_e32 v97, v72
	v_sub_f32_e32 v72, v81, v219
	v_exp_f32_e32 v96, v72
	ds_read2_b64 v[72:75], v225 offset0:12 offset1:14
	v_pk_mov_b32 v[80:81], v[90:91], v[90:91] op_sel:[1,0]
	s_waitcnt lgkmcnt(1)
	v_mfma_f32_32x32x16_bf16 v[2:17], v[76:79], v[68:71], v[2:17]
	v_pk_mov_b32 v[70:71], v[92:93], v[92:93] op_sel:[1,0]
	v_pk_mov_b32 v[76:77], v[96:97], v[96:97] op_sel:[1,0]
	v_cvt_pk_bf16_f32 v69, v70, v71
	v_pk_mov_b32 v[70:71], v[94:95], v[94:95] op_sel:[1,0]
	v_cvt_pk_bf16_f32 v68, v80, v81
	v_cvt_pk_bf16_f32 v70, v70, v71
	v_cvt_pk_bf16_f32 v71, v76, v77
	ds_read2_b64 v[76:79], v226 offset0:44 offset1:46
	s_waitcnt lgkmcnt(1)
	v_mfma_f32_32x32x16_bf16 v[50:65], v[72:75], v[68:71], v[50:65]
	v_add_f32_e32 v72, v198, v199
	v_add_f32_e32 v67, v67, v72
	v_add_f32_e32 v72, v66, v67
	v_add_f32_e64 v66, v82, v90
	v_add_f32_e64 v67, v83, v91
	v_add_f32_e32 v67, v67, v72
	ds_read2_b64 v[72:75], v228 offset0:76 offset1:78
	s_waitcnt lgkmcnt(1)
	v_mfma_f32_32x32x16_bf16 v[34:49], v[76:79], v[68:71], v[34:49]
	v_add_f32_e32 v76, v66, v67
	v_add_f32_e64 v66, v84, v92
	v_add_f32_e64 v67, v85, v93
	v_add_f32_e32 v67, v67, v76
	v_add_f32_e32 v76, v66, v67
	v_pk_add_f32 v[66:67], v[86:87], v[94:95]
	s_nop 0
	v_add_f32_e32 v67, v67, v76
	ds_read2_b64 v[76:79], v224 offset0:108 offset1:110
	s_waitcnt lgkmcnt(1)
	v_mfma_f32_32x32x16_bf16 v[18:33], v[72:75], v[68:71], v[18:33]
	v_add_f32_e32 v72, v66, v67
	v_add_f32_e64 v66, v88, v96
	v_add_f32_e64 v67, v89, v97
	v_add_f32_e32 v67, v67, v72
	v_add_f32_e32 v66, v66, v67
	v_fmac_f32_e32 v66, v214, v0
	v_mov_b32_e32 v214, v66
	s_waitcnt lgkmcnt(0)
	v_mfma_f32_32x32x16_bf16 v[2:17], v[76:79], v[68:71], v[2:17]
	s_andn2_b64 vcc, exec, s[8:9]
	s_cbranch_vccz .LBB0_183
	s_branch .LBB0_184
